# v22 + QKVZ epilogue specialised three ways by tile column range (plain / rope-only / rope+scale): constant selects resolved by register aliasing, dead packed math removed
# baseline (speedup 1.0000x reference)
;     __device__ __forceinline__ void operator()(f32x4 (&acc)[2][2][4][2], const pg8::Unit& u, int wr, int wc, int fr, int fq, LAS unsigned char* lds) const {
;     ...
;                 const int r = u.pm * 256 + ai * 128 + wr * 64 + m * 16 + fr;
;                 const bool lat = r < NLAT;
;                 const int t = r & (SEQ - 1);
;                 const int val = (wc & 1) ? (t & 63) : (t >> 6);
;                 const f32x4 cs = *(const f32x4*)(rope + val * 32 + 4 * fq), sn = *(const f32x4*)(rope + val * 32 + 16 + 4 * fq);
;                 bf16_t* rowp = O + (size_t)r * NQKVZ;
; #pragma unroll
;                 for (int bj = 0; bj < 2; ++bj) {
;                     const int cb = u.pn * 256 + bj * 128 + wc * 32;
;                     f32x4 t1 = acc[ai][bj][m][0], t2 = acc[ai][bj][m][1];
;                     if (cb < 1280 && lat) { const f32x4 o1 = t1 * cs - t2 * sn, o2 = t2 * cs + t1 * sn; t1 = o1; t2 = o2; }
;                     if (cb < 1024) { t1 = t1 * qs; t2 = t2 * qs; }
.LBB0_188:
	s_lshl_b32 s96, s1, 8
	s_or_b32 s96, s96, s83
	s_cmpk_ge_i32 s96, 0x500
	s_cbranch_scc1 .Lqkvz_plain
	s_cmpk_ge_i32 s0, 64
	s_cbranch_scc1 .Lqkvz_generic
	s_cmpk_ge_i32 s96, 0x400
	s_cbranch_scc1 .Lqkvz_ro
	s_branch .Lqkvz_rs

; __device__ __forceinline__ unsigned pk2(float lo, float hi) { f32x2 v = {lo, hi}; nbf2 r = __builtin_convertvector(v, nbf2); return __builtin_bit_cast(unsigned, r); }
;     __device__ __forceinline__ void operator()(f32x4 (&acc)[2][2][4][2], const pg8::Unit& u, int wr, int wc, int fr, int fq, LAS unsigned char* lds) const {
;     ...
;         for (int ai = 0; ai < 2; ++ai)
; #pragma unroll
;             for (int m = 0; m < 4; ++m) {
;                 const int r = u.pm * 256 + ai * 128 + wr * 64 + m * 16 + fr;
;                 const bool lat = r < NLAT;
;                 const int t = r & (SEQ - 1);
;                 const int val = (wc & 1) ? (t & 63) : (t >> 6);
;                 const f32x4 cs = *(const f32x4*)(rope + val * 32 + 4 * fq), sn = *(const f32x4*)(rope + val * 32 + 16 + 4 * fq);
;                 bf16_t* rowp = O + (size_t)r * NQKVZ;
; #pragma unroll
;                 for (int bj = 0; bj < 2; ++bj) {
;                     const int cb = u.pn * 256 + bj * 128 + wc * 32;
;                     f32x4 t1 = acc[ai][bj][m][0], t2 = acc[ai][bj][m][1];
;                     if (cb < 1280 && lat) { const f32x4 o1 = t1 * cs - t2 * sn, o2 = t2 * cs + t1 * sn; t1 = o1; t2 = o2; }
;                     if (cb < 1024) { t1 = t1 * qs; t2 = t2 * qs; }
;                     u32x4 w; w.x = pk2(t1[0], t1[1]); w.y = pk2(t1[2], t1[3]); w.z = pk2(t2[0], t2[1]); w.w = pk2(t2[2], t2[3]);
;                     *(u32x4*)(rowp + cb + 8 * fq) = w;
;                 }
.Lqkvz_rs:
	s_lshl_b32 s55, s0, 8
	s_add_i32 s55, s55, s82
	s_bfe_u32 s0, s55, 0x60006
	v_mov_b32_e32 v158, s0
	v_cndmask_b32_e64 v136, v150, v158, s[2:3]
	v_lshlrev_b32_e32 v136, 7, v136
	v_lshl_add_u64 v[164:165], v[140:141], 0, v[136:137]
	global_load_dwordx4 v[160:163], v[164:165], off offset:64
	s_nop 0
	global_load_dwordx4 v[164:167], v[164:165], off
	s_lshl_b32 s0, s1, 8
	s_or_b32 s8, s0, s83
	v_or_b32_e32 v136, s55, v150
	s_cmpk_lt_i32 s8, 0x500
	v_cmp_gt_i32_e32 vcc, s81, v136
	v_mad_i64_i32 v[168:169], s[0:1], v136, s90, v[138:139]
	s_cselect_b64 s[64:65], -1, 0
	s_and_b64 s[0:1], s[64:65], vcc
	s_cmpk_lt_i32 s8, 0x400
	s_cselect_b64 s[6:7], -1, 0
	s_ashr_i32 s9, s8, 31
	s_lshl_b64 s[70:71], s[8:9], 1
	v_cndmask_b32_e64 v136, v152, v158, s[2:3]
	v_lshlrev_b32_e32 v136, 7, v136
	v_lshl_add_u64 v[170:171], v[140:141], 0, v[136:137]
	s_waitcnt vmcnt(0)
	v_pk_mul_f32 v[172:173], v[122:123], v[162:163]
	v_pk_mul_f32 v[174:175], v[120:121], v[160:161]
	v_pk_mul_f32 v[176:177], v[126:127], v[162:163]
	v_pk_mul_f32 v[178:179], v[124:125], v[160:161]
	v_pk_fma_f32 v[172:173], v[126:127], v[166:167], v[172:173] neg_lo:[0,0,1] neg_hi:[0,0,1]
	v_pk_fma_f32 v[174:175], v[124:125], v[164:165], v[174:175] neg_lo:[0,0,1] neg_hi:[0,0,1]
	v_pk_fma_f32 v[176:177], v[122:123], v[166:167], v[176:177]
	v_pk_fma_f32 v[178:179], v[120:121], v[164:165], v[178:179]
	s_or_b32 s0, s8, 0x80
	v_pk_mul_f32 v[180:181], v[114:115], v[162:163]
	v_pk_mul_f32 v[182:183], v[112:113], v[160:161]
	v_pk_mul_f32 v[162:163], v[118:119], v[162:163]
	v_pk_mul_f32 v[160:161], v[116:117], v[160:161]
	s_cmpk_lt_i32 s0, 0x500
	v_pk_fma_f32 v[180:181], v[118:119], v[166:167], v[180:181] neg_lo:[0,0,1] neg_hi:[0,0,1]
	v_pk_fma_f32 v[182:183], v[116:117], v[164:165], v[182:183] neg_lo:[0,0,1] neg_hi:[0,0,1]
	v_pk_fma_f32 v[162:163], v[114:115], v[166:167], v[162:163]
	v_pk_fma_f32 v[160:161], v[112:113], v[164:165], v[160:161]
	v_pk_mul_f32 v[164:165], v[172:173], s[50:51] op_sel_hi:[1,0]
	v_pk_mul_f32 v[166:167], v[174:175], s[50:51] op_sel_hi:[1,0]
	v_pk_mul_f32 v[172:173], v[178:179], s[50:51] op_sel_hi:[1,0]
	v_pk_mul_f32 v[174:175], v[176:177], s[50:51] op_sel_hi:[1,0]
	s_cselect_b64 s[66:67], -1, 0
	s_and_b64 vcc, s[66:67], vcc
	v_cvt_pk_bf16_f32 v120, v166, v167
	v_cvt_pk_bf16_f32 v121, v164, v165
	v_cvt_pk_bf16_f32 v122, v172, v173
	v_cvt_pk_bf16_f32 v123, v174, v175
	v_lshl_add_u64 v[124:125], v[168:169], 0, s[70:71]
	s_cmpk_lt_i32 s0, 0x400
	global_store_dwordx4 v[124:125], v[120:123], off
	s_nop 1
	v_pk_mul_f32 v[126:127], v[160:161], s[50:51] op_sel_hi:[1,0]
	v_pk_mul_f32 v[160:161], v[162:163], s[50:51] op_sel_hi:[1,0]
	v_pk_mul_f32 v[120:121], v[182:183], s[50:51] op_sel_hi:[1,0]
	v_pk_mul_f32 v[122:123], v[180:181], s[50:51] op_sel_hi:[1,0]
	s_cselect_b64 s[8:9], -1, 0
	v_mov_b32_e32 v116, v120
	v_mov_b32_e32 v117, v121
	v_cvt_pk_bf16_f32 v112, v116, v117
	v_cvt_pk_bf16_f32 v113, v122, v123
	v_cvt_pk_bf16_f32 v114, v126, v127
	v_cvt_pk_bf16_f32 v115, v160, v161
	global_store_dwordx4 v[124:125], v[112:115], off offset:256
	s_nop 1
	global_load_dwordx4 v[112:115], v[170:171], off offset:64
	s_nop 0
	global_load_dwordx4 v[116:119], v[170:171], off
	v_or_b32_e32 v120, s55, v152
	v_cmp_gt_i32_e32 vcc, s81, v120
	v_mad_i64_i32 v[120:121], s[0:1], v120, s90, v[138:139]
	s_and_b64 s[0:1], s[64:65], vcc
	s_and_b64 vcc, s[66:67], vcc
	v_cndmask_b32_e64 v122, v153, v158, s[2:3]
	v_lshlrev_b32_e32 v136, 7, v122
	v_lshl_add_u64 v[120:121], v[120:121], 0, s[70:71]
	v_lshl_add_u64 v[122:123], v[140:141], 0, v[136:137]
	s_waitcnt vmcnt(1)
	v_pk_mul_f32 v[124:125], v[106:107], v[114:115]
	v_pk_mul_f32 v[126:127], v[104:105], v[112:113]
	v_pk_mul_f32 v[160:161], v[110:111], v[114:115]
	v_pk_mul_f32 v[162:163], v[108:109], v[112:113]
	v_pk_mul_f32 v[164:165], v[98:99], v[114:115]
	v_pk_mul_f32 v[166:167], v[96:97], v[112:113]
	v_pk_mul_f32 v[114:115], v[102:103], v[114:115]
	v_pk_mul_f32 v[112:113], v[100:101], v[112:113]
	s_waitcnt vmcnt(0)
	v_pk_fma_f32 v[124:125], v[110:111], v[118:119], v[124:125] neg_lo:[0,0,1] neg_hi:[0,0,1]
	v_pk_fma_f32 v[126:127], v[108:109], v[116:117], v[126:127] neg_lo:[0,0,1] neg_hi:[0,0,1]
	v_pk_fma_f32 v[160:161], v[106:107], v[118:119], v[160:161]
	v_pk_fma_f32 v[162:163], v[104:105], v[116:117], v[162:163]
	v_pk_fma_f32 v[164:165], v[102:103], v[118:119], v[164:165] neg_lo:[0,0,1] neg_hi:[0,0,1]
	v_pk_fma_f32 v[166:167], v[100:101], v[116:117], v[166:167] neg_lo:[0,0,1] neg_hi:[0,0,1]
	v_pk_fma_f32 v[114:115], v[98:99], v[118:119], v[114:115]
	v_pk_fma_f32 v[112:113], v[96:97], v[116:117], v[112:113]
	v_mov_b32_e32 v96, v112
	v_mov_b32_e32 v97, v113
	v_pk_mul_f32 v[112:113], v[126:127], s[50:51] op_sel_hi:[1,0]
	v_mov_b32_e32 v98, v114
	v_mov_b32_e32 v99, v115
	v_pk_mul_f32 v[114:115], v[124:125], s[50:51] op_sel_hi:[1,0]
	v_pk_mul_f32 v[116:117], v[162:163], s[50:51] op_sel_hi:[1,0]
	v_pk_mul_f32 v[118:119], v[160:161], s[50:51] op_sel_hi:[1,0]
	v_pk_mul_f32 v[124:125], v[166:167], s[50:51] op_sel_hi:[1,0]
	v_pk_mul_f32 v[126:127], v[164:165], s[50:51] op_sel_hi:[1,0]
	v_pk_mul_f32 v[160:161], v[96:97], s[50:51] op_sel_hi:[1,0]
	v_pk_mul_f32 v[162:163], v[98:99], s[50:51] op_sel_hi:[1,0]
	v_mov_b32_e32 v108, v112
	v_mov_b32_e32 v109, v113
	v_mov_b32_e32 v110, v114
	v_mov_b32_e32 v111, v115
	v_cvt_pk_bf16_f32 v96, v108, v109
	v_cvt_pk_bf16_f32 v97, v110, v111
	v_cvt_pk_bf16_f32 v98, v116, v117
	v_cvt_pk_bf16_f32 v99, v118, v119
	v_cvt_pk_bf16_f32 v100, v124, v125
	v_cvt_pk_bf16_f32 v101, v126, v127
	v_cvt_pk_bf16_f32 v102, v160, v161
	v_cvt_pk_bf16_f32 v103, v162, v163
	global_store_dwordx4 v[120:121], v[96:99], off
	s_nop 1
	global_store_dwordx4 v[120:121], v[100:103], off offset:256
	s_nop 1
	global_load_dwordx4 v[96:99], v[122:123], off offset:64
	s_nop 0
	global_load_dwordx4 v[100:103], v[122:123], off
	v_or_b32_e32 v104, s55, v153
	v_cmp_gt_i32_e32 vcc, s81, v104
	v_mad_i64_i32 v[104:105], s[0:1], v104, s90, v[138:139]
	s_and_b64 s[0:1], s[64:65], vcc
	s_and_b64 vcc, s[66:67], vcc
	v_cndmask_b32_e64 v106, v154, v158, s[2:3]
	v_lshlrev_b32_e32 v136, 7, v106
	v_lshl_add_u64 v[104:105], v[104:105], 0, s[70:71]
	v_lshl_add_u64 v[106:107], v[140:141], 0, v[136:137]
	s_waitcnt vmcnt(1)
; __device__ __forceinline__ unsigned pk2(float lo, float hi) { f32x2 v = {lo, hi}; nbf2 r = __builtin_convertvector(v, nbf2); return __builtin_bit_cast(unsigned, r); }
;     __device__ __forceinline__ void operator()(f32x4 (&acc)[2][2][4][2], const pg8::Unit& u, int wr, int wc, int fr, int fq, LAS unsigned char* lds) const {
;     ...
;         for (int ai = 0; ai < 2; ++ai)
; #pragma unroll
;             for (int m = 0; m < 4; ++m) {
;                 const int r = u.pm * 256 + ai * 128 + wr * 64 + m * 16 + fr;
;                 const bool lat = r < NLAT;
;                 const int t = r & (SEQ - 1);
;                 const int val = (wc & 1) ? (t & 63) : (t >> 6);
;                 const f32x4 cs = *(const f32x4*)(rope + val * 32 + 4 * fq), sn = *(const f32x4*)(rope + val * 32 + 16 + 4 * fq);
;                 bf16_t* rowp = O + (size_t)r * NQKVZ;
; #pragma unroll
;                 for (int bj = 0; bj < 2; ++bj) {
;                     const int cb = u.pn * 256 + bj * 128 + wc * 32;
;                     f32x4 t1 = acc[ai][bj][m][0], t2 = acc[ai][bj][m][1];
;                     if (cb < 1280 && lat) { const f32x4 o1 = t1 * cs - t2 * sn, o2 = t2 * cs + t1 * sn; t1 = o1; t2 = o2; }
;                     if (cb < 1024) { t1 = t1 * qs; t2 = t2 * qs; }
;                     u32x4 w; w.x = pk2(t1[0], t1[1]); w.y = pk2(t1[2], t1[3]); w.z = pk2(t2[0], t2[1]); w.w = pk2(t2[2], t2[3]);
;                     *(u32x4*)(rowp + cb + 8 * fq) = w;
;                 }
	v_pk_mul_f32 v[108:109], v[90:91], v[98:99]
	v_pk_mul_f32 v[110:111], v[88:89], v[96:97]
	v_pk_mul_f32 v[112:113], v[94:95], v[98:99]
	v_pk_mul_f32 v[114:115], v[92:93], v[96:97]
	v_pk_mul_f32 v[116:117], v[82:83], v[98:99]
	v_pk_mul_f32 v[118:119], v[80:81], v[96:97]
	v_pk_mul_f32 v[98:99], v[86:87], v[98:99]
	v_pk_mul_f32 v[96:97], v[84:85], v[96:97]
	s_waitcnt vmcnt(0)
	v_pk_fma_f32 v[108:109], v[94:95], v[102:103], v[108:109] neg_lo:[0,0,1] neg_hi:[0,0,1]
	v_pk_fma_f32 v[110:111], v[92:93], v[100:101], v[110:111] neg_lo:[0,0,1] neg_hi:[0,0,1]
	v_pk_fma_f32 v[112:113], v[90:91], v[102:103], v[112:113]
	v_pk_fma_f32 v[114:115], v[88:89], v[100:101], v[114:115]
	v_pk_fma_f32 v[116:117], v[86:87], v[102:103], v[116:117] neg_lo:[0,0,1] neg_hi:[0,0,1]
	v_pk_fma_f32 v[118:119], v[84:85], v[100:101], v[118:119] neg_lo:[0,0,1] neg_hi:[0,0,1]
	v_pk_fma_f32 v[98:99], v[82:83], v[102:103], v[98:99]
	v_pk_fma_f32 v[96:97], v[80:81], v[100:101], v[96:97]
	v_mov_b32_e32 v80, v96
	v_mov_b32_e32 v81, v97
	v_pk_mul_f32 v[96:97], v[110:111], s[50:51] op_sel_hi:[1,0]
	v_mov_b32_e32 v82, v98
	v_mov_b32_e32 v83, v99
	v_pk_mul_f32 v[98:99], v[108:109], s[50:51] op_sel_hi:[1,0]
	v_pk_mul_f32 v[100:101], v[114:115], s[50:51] op_sel_hi:[1,0]
	v_pk_mul_f32 v[102:103], v[112:113], s[50:51] op_sel_hi:[1,0]
	v_pk_mul_f32 v[108:109], v[118:119], s[50:51] op_sel_hi:[1,0]
	v_pk_mul_f32 v[110:111], v[116:117], s[50:51] op_sel_hi:[1,0]
	v_pk_mul_f32 v[112:113], v[80:81], s[50:51] op_sel_hi:[1,0]
	v_pk_mul_f32 v[114:115], v[82:83], s[50:51] op_sel_hi:[1,0]
	v_mov_b32_e32 v92, v96
	v_mov_b32_e32 v93, v97
	v_mov_b32_e32 v94, v98
	v_mov_b32_e32 v95, v99
	v_cvt_pk_bf16_f32 v80, v92, v93
	v_cvt_pk_bf16_f32 v81, v94, v95
	v_cvt_pk_bf16_f32 v82, v100, v101
	v_cvt_pk_bf16_f32 v83, v102, v103
	v_cvt_pk_bf16_f32 v84, v108, v109
	v_cvt_pk_bf16_f32 v85, v110, v111
	v_cvt_pk_bf16_f32 v86, v112, v113
	v_cvt_pk_bf16_f32 v87, v114, v115
	global_store_dwordx4 v[104:105], v[80:83], off
	s_nop 1
	global_store_dwordx4 v[104:105], v[84:87], off offset:256
	s_nop 1
	global_load_dwordx4 v[82:85], v[106:107], off offset:64
	s_nop 0
	global_load_dwordx4 v[86:89], v[106:107], off
	v_or_b32_e32 v80, s55, v154
	v_cmp_gt_i32_e32 vcc, s81, v80
	v_mad_i64_i32 v[80:81], s[0:1], v80, s90, v[138:139]
	s_addk_i32 s55, 0x80
	s_bfe_u32 s0, s55, 0x60006
	v_lshl_add_u64 v[90:91], v[80:81], 0, s[70:71]
	v_mov_b32_e32 v80, s0
	s_and_b64 s[0:1], s[64:65], vcc
	s_and_b64 vcc, s[66:67], vcc
	v_cndmask_b32_e64 v81, v150, v80, s[2:3]
	v_lshlrev_b32_e32 v136, 7, v81
	v_lshl_add_u64 v[92:93], v[140:141], 0, v[136:137]
	s_waitcnt vmcnt(1)
	v_pk_mul_f32 v[94:95], v[74:75], v[84:85]
	v_pk_mul_f32 v[96:97], v[72:73], v[82:83]
	v_pk_mul_f32 v[98:99], v[78:79], v[84:85]
	v_pk_mul_f32 v[100:101], v[76:77], v[82:83]
	v_pk_mul_f32 v[102:103], v[66:67], v[84:85]
	v_pk_mul_f32 v[104:105], v[64:65], v[82:83]
	v_pk_mul_f32 v[84:85], v[70:71], v[84:85]
	v_pk_mul_f32 v[82:83], v[68:69], v[82:83]
	s_waitcnt vmcnt(0)
	v_pk_fma_f32 v[94:95], v[78:79], v[88:89], v[94:95] neg_lo:[0,0,1] neg_hi:[0,0,1]
	v_pk_fma_f32 v[96:97], v[76:77], v[86:87], v[96:97] neg_lo:[0,0,1] neg_hi:[0,0,1]
	v_pk_fma_f32 v[98:99], v[74:75], v[88:89], v[98:99]
	v_pk_fma_f32 v[100:101], v[72:73], v[86:87], v[100:101]
	v_pk_fma_f32 v[102:103], v[70:71], v[88:89], v[102:103] neg_lo:[0,0,1] neg_hi:[0,0,1]
	v_pk_fma_f32 v[104:105], v[68:69], v[86:87], v[104:105] neg_lo:[0,0,1] neg_hi:[0,0,1]
	v_pk_fma_f32 v[84:85], v[66:67], v[88:89], v[84:85]
	v_pk_fma_f32 v[82:83], v[64:65], v[86:87], v[82:83]
	v_mov_b32_e32 v64, v82
	v_mov_b32_e32 v65, v83
	v_pk_mul_f32 v[82:83], v[96:97], s[50:51] op_sel_hi:[1,0]
	v_mov_b32_e32 v66, v84
	v_mov_b32_e32 v67, v85
	v_pk_mul_f32 v[84:85], v[94:95], s[50:51] op_sel_hi:[1,0]
	v_pk_mul_f32 v[86:87], v[100:101], s[50:51] op_sel_hi:[1,0]
	v_pk_mul_f32 v[88:89], v[98:99], s[50:51] op_sel_hi:[1,0]
	v_pk_mul_f32 v[94:95], v[104:105], s[50:51] op_sel_hi:[1,0]
	v_pk_mul_f32 v[96:97], v[102:103], s[50:51] op_sel_hi:[1,0]
	v_pk_mul_f32 v[98:99], v[64:65], s[50:51] op_sel_hi:[1,0]
	v_pk_mul_f32 v[100:101], v[66:67], s[50:51] op_sel_hi:[1,0]
	v_mov_b32_e32 v76, v82
	v_mov_b32_e32 v77, v83
	v_mov_b32_e32 v78, v84
	v_cvt_pk_bf16_f32 v64, v76, v77
	v_cvt_pk_bf16_f32 v65, v78, v85
	v_cvt_pk_bf16_f32 v66, v86, v87
	v_cvt_pk_bf16_f32 v67, v88, v89
	v_cvt_pk_bf16_f32 v68, v94, v95
	v_cvt_pk_bf16_f32 v69, v96, v97
	v_cvt_pk_bf16_f32 v70, v98, v99
	v_cvt_pk_bf16_f32 v71, v100, v101
	global_store_dwordx4 v[90:91], v[64:67], off
	s_nop 1
	global_store_dwordx4 v[90:91], v[68:71], off offset:256
	s_nop 1
	global_load_dwordx4 v[64:67], v[92:93], off offset:64
	s_nop 0
	global_load_dwordx4 v[68:71], v[92:93], off
	v_or_b32_e32 v72, s55, v150
	v_cmp_gt_i32_e32 vcc, s81, v72
	v_mad_i64_i32 v[72:73], s[0:1], v72, s90, v[138:139]
	s_and_b64 s[0:1], s[64:65], vcc
	s_and_b64 vcc, s[66:67], vcc
	v_cndmask_b32_e64 v74, v152, v80, s[2:3]
	v_lshl_add_u64 v[72:73], v[72:73], 0, s[70:71]
	v_lshlrev_b32_e32 v136, 7, v74
	v_lshl_add_u64 v[74:75], v[140:141], 0, v[136:137]
	s_waitcnt vmcnt(1)
	v_pk_mul_f32 v[76:77], v[58:59], v[66:67]
	v_pk_mul_f32 v[78:79], v[56:57], v[64:65]
	v_pk_mul_f32 v[82:83], v[62:63], v[66:67]
	v_pk_mul_f32 v[84:85], v[60:61], v[64:65]
	v_pk_mul_f32 v[86:87], v[50:51], v[66:67]
	v_pk_mul_f32 v[88:89], v[48:49], v[64:65]
	v_pk_mul_f32 v[66:67], v[54:55], v[66:67]
	v_pk_mul_f32 v[64:65], v[52:53], v[64:65]
	s_waitcnt vmcnt(0)
; __device__ __forceinline__ unsigned pk2(float lo, float hi) { f32x2 v = {lo, hi}; nbf2 r = __builtin_convertvector(v, nbf2); return __builtin_bit_cast(unsigned, r); }
;     __device__ __forceinline__ void operator()(f32x4 (&acc)[2][2][4][2], const pg8::Unit& u, int wr, int wc, int fr, int fq, LAS unsigned char* lds) const {
;     ...
;         for (int ai = 0; ai < 2; ++ai)
; #pragma unroll
;             for (int m = 0; m < 4; ++m) {
;                 const int r = u.pm * 256 + ai * 128 + wr * 64 + m * 16 + fr;
;                 const bool lat = r < NLAT;
;                 const int t = r & (SEQ - 1);
;                 const int val = (wc & 1) ? (t & 63) : (t >> 6);
;                 const f32x4 cs = *(const f32x4*)(rope + val * 32 + 4 * fq), sn = *(const f32x4*)(rope + val * 32 + 16 + 4 * fq);
;                 bf16_t* rowp = O + (size_t)r * NQKVZ;
; #pragma unroll
;                 for (int bj = 0; bj < 2; ++bj) {
;                     const int cb = u.pn * 256 + bj * 128 + wc * 32;
;                     f32x4 t1 = acc[ai][bj][m][0], t2 = acc[ai][bj][m][1];
;                     if (cb < 1280 && lat) { const f32x4 o1 = t1 * cs - t2 * sn, o2 = t2 * cs + t1 * sn; t1 = o1; t2 = o2; }
;                     if (cb < 1024) { t1 = t1 * qs; t2 = t2 * qs; }
;                     u32x4 w; w.x = pk2(t1[0], t1[1]); w.y = pk2(t1[2], t1[3]); w.z = pk2(t2[0], t2[1]); w.w = pk2(t2[2], t2[3]);
;                     *(u32x4*)(rowp + cb + 8 * fq) = w;
;                 }
	v_pk_fma_f32 v[76:77], v[62:63], v[70:71], v[76:77] neg_lo:[0,0,1] neg_hi:[0,0,1]
	v_pk_fma_f32 v[78:79], v[60:61], v[68:69], v[78:79] neg_lo:[0,0,1] neg_hi:[0,0,1]
	v_pk_fma_f32 v[82:83], v[58:59], v[70:71], v[82:83]
	v_pk_fma_f32 v[84:85], v[56:57], v[68:69], v[84:85]
	v_pk_fma_f32 v[86:87], v[54:55], v[70:71], v[86:87] neg_lo:[0,0,1] neg_hi:[0,0,1]
	v_pk_fma_f32 v[88:89], v[52:53], v[68:69], v[88:89] neg_lo:[0,0,1] neg_hi:[0,0,1]
	v_pk_fma_f32 v[66:67], v[50:51], v[70:71], v[66:67]
	v_pk_fma_f32 v[64:65], v[48:49], v[68:69], v[64:65]
	v_mov_b32_e32 v48, v64
	v_mov_b32_e32 v49, v65
	v_pk_mul_f32 v[64:65], v[78:79], s[50:51] op_sel_hi:[1,0]
	v_mov_b32_e32 v50, v66
	v_mov_b32_e32 v51, v67
	v_pk_mul_f32 v[66:67], v[76:77], s[50:51] op_sel_hi:[1,0]
	v_pk_mul_f32 v[68:69], v[84:85], s[50:51] op_sel_hi:[1,0]
	v_pk_mul_f32 v[70:71], v[82:83], s[50:51] op_sel_hi:[1,0]
	v_pk_mul_f32 v[76:77], v[88:89], s[50:51] op_sel_hi:[1,0]
	v_pk_mul_f32 v[78:79], v[86:87], s[50:51] op_sel_hi:[1,0]
	v_pk_mul_f32 v[82:83], v[48:49], s[50:51] op_sel_hi:[1,0]
	v_pk_mul_f32 v[84:85], v[50:51], s[50:51] op_sel_hi:[1,0]
	v_mov_b32_e32 v60, v64
	v_mov_b32_e32 v61, v65
	v_mov_b32_e32 v62, v66
	v_mov_b32_e32 v63, v67
	v_cvt_pk_bf16_f32 v48, v60, v61
	v_cvt_pk_bf16_f32 v49, v62, v63
	v_cvt_pk_bf16_f32 v50, v68, v69
	v_cvt_pk_bf16_f32 v51, v70, v71
	v_cvt_pk_bf16_f32 v52, v76, v77
	v_cvt_pk_bf16_f32 v53, v78, v79
	v_cvt_pk_bf16_f32 v54, v82, v83
	v_cvt_pk_bf16_f32 v55, v84, v85
	global_store_dwordx4 v[72:73], v[48:51], off
	s_nop 1
	global_store_dwordx4 v[72:73], v[52:55], off offset:256
	s_nop 1
	global_load_dwordx4 v[48:51], v[74:75], off offset:64
	s_nop 0
	global_load_dwordx4 v[52:55], v[74:75], off
	v_or_b32_e32 v56, s55, v152
	v_cmp_gt_i32_e32 vcc, s81, v56
	v_mad_i64_i32 v[56:57], s[0:1], v56, s90, v[138:139]
	s_and_b64 s[0:1], s[64:65], vcc
	s_and_b64 vcc, s[66:67], vcc
	v_cndmask_b32_e64 v58, v153, v80, s[2:3]
	v_lshl_add_u64 v[56:57], v[56:57], 0, s[70:71]
	v_lshlrev_b32_e32 v136, 7, v58
	v_lshl_add_u64 v[58:59], v[140:141], 0, v[136:137]
	s_waitcnt vmcnt(1)
	v_pk_mul_f32 v[60:61], v[42:43], v[50:51]
	v_pk_mul_f32 v[62:63], v[40:41], v[48:49]
	v_pk_mul_f32 v[64:65], v[46:47], v[50:51]
	v_pk_mul_f32 v[66:67], v[44:45], v[48:49]
	v_pk_mul_f32 v[68:69], v[34:35], v[50:51]
	v_pk_mul_f32 v[70:71], v[32:33], v[48:49]
	v_pk_mul_f32 v[50:51], v[38:39], v[50:51]
	v_pk_mul_f32 v[48:49], v[36:37], v[48:49]
	s_waitcnt vmcnt(0)
	v_pk_fma_f32 v[60:61], v[46:47], v[54:55], v[60:61] neg_lo:[0,0,1] neg_hi:[0,0,1]
	v_pk_fma_f32 v[62:63], v[44:45], v[52:53], v[62:63] neg_lo:[0,0,1] neg_hi:[0,0,1]
	v_pk_fma_f32 v[64:65], v[42:43], v[54:55], v[64:65]
	v_pk_fma_f32 v[66:67], v[40:41], v[52:53], v[66:67]
	v_pk_fma_f32 v[68:69], v[38:39], v[54:55], v[68:69] neg_lo:[0,0,1] neg_hi:[0,0,1]
	v_pk_fma_f32 v[70:71], v[36:37], v[52:53], v[70:71] neg_lo:[0,0,1] neg_hi:[0,0,1]
	v_pk_fma_f32 v[50:51], v[34:35], v[54:55], v[50:51]
	v_pk_fma_f32 v[48:49], v[32:33], v[52:53], v[48:49]
	v_mov_b32_e32 v32, v48
	v_mov_b32_e32 v33, v49
	v_pk_mul_f32 v[48:49], v[62:63], s[50:51] op_sel_hi:[1,0]
	v_mov_b32_e32 v34, v50
	v_mov_b32_e32 v35, v51
	v_pk_mul_f32 v[50:51], v[60:61], s[50:51] op_sel_hi:[1,0]
	v_pk_mul_f32 v[52:53], v[66:67], s[50:51] op_sel_hi:[1,0]
	v_pk_mul_f32 v[54:55], v[64:65], s[50:51] op_sel_hi:[1,0]
	v_pk_mul_f32 v[60:61], v[70:71], s[50:51] op_sel_hi:[1,0]
	v_pk_mul_f32 v[62:63], v[68:69], s[50:51] op_sel_hi:[1,0]
	v_pk_mul_f32 v[64:65], v[32:33], s[50:51] op_sel_hi:[1,0]
	v_pk_mul_f32 v[66:67], v[34:35], s[50:51] op_sel_hi:[1,0]
	v_mov_b32_e32 v44, v48
	v_mov_b32_e32 v45, v49
	v_mov_b32_e32 v46, v50
	v_mov_b32_e32 v47, v51
	v_cvt_pk_bf16_f32 v32, v44, v45
	v_cvt_pk_bf16_f32 v33, v46, v47
	v_cvt_pk_bf16_f32 v34, v52, v53
	v_cvt_pk_bf16_f32 v35, v54, v55
	v_cvt_pk_bf16_f32 v36, v60, v61
	v_cvt_pk_bf16_f32 v37, v62, v63
	v_cvt_pk_bf16_f32 v38, v64, v65
	v_cvt_pk_bf16_f32 v39, v66, v67
	global_store_dwordx4 v[56:57], v[32:35], off
	s_nop 1
	global_store_dwordx4 v[56:57], v[36:39], off offset:256
	s_nop 1
	global_load_dwordx4 v[32:35], v[58:59], off offset:64
	s_nop 0
	global_load_dwordx4 v[36:39], v[58:59], off
	v_or_b32_e32 v40, s55, v153
	v_cmp_gt_i32_e32 vcc, s81, v40
	v_mad_i64_i32 v[40:41], s[0:1], v40, s90, v[138:139]
	s_and_b64 s[0:1], s[64:65], vcc
	s_and_b64 vcc, s[66:67], vcc
	v_cndmask_b32_e64 v42, v154, v80, s[2:3]
	v_lshl_add_u64 v[40:41], v[40:41], 0, s[70:71]
	v_lshlrev_b32_e32 v136, 7, v42
	v_lshl_add_u64 v[42:43], v[140:141], 0, v[136:137]
	s_waitcnt vmcnt(1)
	v_pk_mul_f32 v[44:45], v[26:27], v[34:35]
	v_pk_mul_f32 v[46:47], v[24:25], v[32:33]
	v_pk_mul_f32 v[48:49], v[30:31], v[34:35]
	v_pk_mul_f32 v[50:51], v[28:29], v[32:33]
	v_pk_mul_f32 v[52:53], v[18:19], v[34:35]
	v_pk_mul_f32 v[54:55], v[16:17], v[32:33]
	v_pk_mul_f32 v[34:35], v[22:23], v[34:35]
	v_pk_mul_f32 v[32:33], v[20:21], v[32:33]
	s_waitcnt vmcnt(0)
; __device__ __forceinline__ unsigned pk2(float lo, float hi) { f32x2 v = {lo, hi}; nbf2 r = __builtin_convertvector(v, nbf2); return __builtin_bit_cast(unsigned, r); }
;     __device__ __forceinline__ void operator()(f32x4 (&acc)[2][2][4][2], const pg8::Unit& u, int wr, int wc, int fr, int fq, LAS unsigned char* lds) const {
;     ...
;         for (int ai = 0; ai < 2; ++ai)
; #pragma unroll
;             for (int m = 0; m < 4; ++m) {
;                 const int r = u.pm * 256 + ai * 128 + wr * 64 + m * 16 + fr;
;                 const bool lat = r < NLAT;
;                 const int t = r & (SEQ - 1);
;                 const int val = (wc & 1) ? (t & 63) : (t >> 6);
;                 const f32x4 cs = *(const f32x4*)(rope + val * 32 + 4 * fq), sn = *(const f32x4*)(rope + val * 32 + 16 + 4 * fq);
;                 bf16_t* rowp = O + (size_t)r * NQKVZ;
; #pragma unroll
;                 for (int bj = 0; bj < 2; ++bj) {
;                     const int cb = u.pn * 256 + bj * 128 + wc * 32;
;                     f32x4 t1 = acc[ai][bj][m][0], t2 = acc[ai][bj][m][1];
;                     if (cb < 1280 && lat) { const f32x4 o1 = t1 * cs - t2 * sn, o2 = t2 * cs + t1 * sn; t1 = o1; t2 = o2; }
;                     if (cb < 1024) { t1 = t1 * qs; t2 = t2 * qs; }
;                     u32x4 w; w.x = pk2(t1[0], t1[1]); w.y = pk2(t1[2], t1[3]); w.z = pk2(t2[0], t2[1]); w.w = pk2(t2[2], t2[3]);
;                     *(u32x4*)(rowp + cb + 8 * fq) = w;
;                 }
	v_pk_fma_f32 v[44:45], v[30:31], v[38:39], v[44:45] neg_lo:[0,0,1] neg_hi:[0,0,1]
	v_pk_fma_f32 v[46:47], v[28:29], v[36:37], v[46:47] neg_lo:[0,0,1] neg_hi:[0,0,1]
	v_pk_fma_f32 v[48:49], v[26:27], v[38:39], v[48:49]
	v_pk_fma_f32 v[50:51], v[24:25], v[36:37], v[50:51]
	v_pk_fma_f32 v[52:53], v[22:23], v[38:39], v[52:53] neg_lo:[0,0,1] neg_hi:[0,0,1]
	v_pk_fma_f32 v[54:55], v[20:21], v[36:37], v[54:55] neg_lo:[0,0,1] neg_hi:[0,0,1]
	v_pk_fma_f32 v[34:35], v[18:19], v[38:39], v[34:35]
	v_pk_fma_f32 v[32:33], v[16:17], v[36:37], v[32:33]
	v_mov_b32_e32 v16, v32
	v_mov_b32_e32 v17, v33
	v_pk_mul_f32 v[32:33], v[46:47], s[50:51] op_sel_hi:[1,0]
	v_mov_b32_e32 v18, v34
	v_mov_b32_e32 v19, v35
	v_pk_mul_f32 v[34:35], v[44:45], s[50:51] op_sel_hi:[1,0]
	v_pk_mul_f32 v[36:37], v[50:51], s[50:51] op_sel_hi:[1,0]
	v_pk_mul_f32 v[38:39], v[48:49], s[50:51] op_sel_hi:[1,0]
	v_pk_mul_f32 v[44:45], v[54:55], s[50:51] op_sel_hi:[1,0]
	v_pk_mul_f32 v[46:47], v[52:53], s[50:51] op_sel_hi:[1,0]
	v_pk_mul_f32 v[48:49], v[16:17], s[50:51] op_sel_hi:[1,0]
	v_pk_mul_f32 v[50:51], v[18:19], s[50:51] op_sel_hi:[1,0]
	v_mov_b32_e32 v28, v32
	v_mov_b32_e32 v29, v33
	v_mov_b32_e32 v30, v34
	v_mov_b32_e32 v31, v35
	v_cvt_pk_bf16_f32 v16, v28, v29
	v_cvt_pk_bf16_f32 v17, v30, v31
	v_cvt_pk_bf16_f32 v18, v36, v37
	v_cvt_pk_bf16_f32 v19, v38, v39
	v_cvt_pk_bf16_f32 v20, v44, v45
	v_cvt_pk_bf16_f32 v21, v46, v47
	v_cvt_pk_bf16_f32 v22, v48, v49
	v_cvt_pk_bf16_f32 v23, v50, v51
	global_store_dwordx4 v[40:41], v[16:19], off
	s_nop 1
	global_store_dwordx4 v[40:41], v[20:23], off offset:256
	s_nop 1
	global_load_dwordx4 v[16:19], v[42:43], off offset:64
	s_nop 0
	global_load_dwordx4 v[20:23], v[42:43], off
	v_or_b32_e32 v24, s55, v154
	s_andn2_b64 vcc, exec, s[4:5]
	v_cmp_gt_i32_e64 s[0:1], s81, v24
	v_mad_i64_i32 v[24:25], s[4:5], v24, s90, v[138:139]
	s_and_b64 s[4:5], s[64:65], s[0:1]
	s_and_b64 s[0:1], s[66:67], s[0:1]
	v_lshl_add_u64 v[24:25], v[24:25], 0, s[70:71]
	s_waitcnt vmcnt(1)
	v_pk_mul_f32 v[26:27], v[10:11], v[18:19]
	v_pk_mul_f32 v[28:29], v[8:9], v[16:17]
	v_pk_mul_f32 v[30:31], v[14:15], v[18:19]
	v_pk_mul_f32 v[32:33], v[12:13], v[16:17]
	v_pk_mul_f32 v[34:35], v[2:3], v[18:19]
	v_pk_mul_f32 v[36:37], v[0:1], v[16:17]
	v_pk_mul_f32 v[18:19], v[6:7], v[18:19]
	v_pk_mul_f32 v[16:17], v[4:5], v[16:17]
	s_waitcnt vmcnt(0)
	v_pk_fma_f32 v[26:27], v[14:15], v[22:23], v[26:27] neg_lo:[0,0,1] neg_hi:[0,0,1]
	v_pk_fma_f32 v[28:29], v[12:13], v[20:21], v[28:29] neg_lo:[0,0,1] neg_hi:[0,0,1]
	v_pk_fma_f32 v[30:31], v[10:11], v[22:23], v[30:31]
	v_pk_fma_f32 v[32:33], v[8:9], v[20:21], v[32:33]
	v_pk_fma_f32 v[34:35], v[6:7], v[22:23], v[34:35] neg_lo:[0,0,1] neg_hi:[0,0,1]
	v_pk_fma_f32 v[36:37], v[4:5], v[20:21], v[36:37] neg_lo:[0,0,1] neg_hi:[0,0,1]
	v_pk_fma_f32 v[18:19], v[2:3], v[22:23], v[18:19]
	v_pk_fma_f32 v[16:17], v[0:1], v[20:21], v[16:17]
	v_mov_b32_e32 v0, v16
	v_mov_b32_e32 v1, v17
	v_pk_mul_f32 v[16:17], v[28:29], s[50:51] op_sel_hi:[1,0]
	v_mov_b32_e32 v2, v18
	v_mov_b32_e32 v3, v19
	v_pk_mul_f32 v[18:19], v[26:27], s[50:51] op_sel_hi:[1,0]
	v_pk_mul_f32 v[20:21], v[32:33], s[50:51] op_sel_hi:[1,0]
	v_pk_mul_f32 v[22:23], v[30:31], s[50:51] op_sel_hi:[1,0]
	v_pk_mul_f32 v[26:27], v[36:37], s[50:51] op_sel_hi:[1,0]
	v_pk_mul_f32 v[28:29], v[34:35], s[50:51] op_sel_hi:[1,0]
	v_pk_mul_f32 v[30:31], v[0:1], s[50:51] op_sel_hi:[1,0]
	v_pk_mul_f32 v[32:33], v[2:3], s[50:51] op_sel_hi:[1,0]
	v_mov_b32_e32 v12, v16
	v_mov_b32_e32 v13, v17
	v_mov_b32_e32 v14, v18
	v_mov_b32_e32 v15, v19
	v_cvt_pk_bf16_f32 v0, v12, v13
	v_cvt_pk_bf16_f32 v1, v14, v15
	v_cvt_pk_bf16_f32 v2, v20, v21
	v_cvt_pk_bf16_f32 v3, v22, v23
	s_mov_b64 s[0:1], -1
	v_cvt_pk_bf16_f32 v4, v26, v27
	v_cvt_pk_bf16_f32 v5, v28, v29
	v_cvt_pk_bf16_f32 v6, v30, v31
	v_cvt_pk_bf16_f32 v7, v32, v33
	global_store_dwordx4 v[24:25], v[0:3], off
	s_nop 1
	global_store_dwordx4 v[24:25], v[4:7], off offset:256
	s_nop 1
	s_cbranch_vccnz .LBB0_181
	s_andn2_b64 vcc, exec, s[42:43]
	s_cbranch_vccnz .LBB0_180
	s_barrier
	s_branch .LBB0_180
.Lqkvz_ro:
	s_lshl_b32 s55, s0, 8
	s_add_i32 s55, s55, s82
	s_bfe_u32 s0, s55, 0x60006
	v_mov_b32_e32 v158, s0
	v_cndmask_b32_e64 v136, v150, v158, s[2:3]
	v_lshlrev_b32_e32 v136, 7, v136
	v_lshl_add_u64 v[164:165], v[140:141], 0, v[136:137]
	global_load_dwordx4 v[160:163], v[164:165], off offset:64
	s_nop 0
	global_load_dwordx4 v[164:167], v[164:165], off
	s_lshl_b32 s0, s1, 8
	s_or_b32 s8, s0, s83
	v_or_b32_e32 v136, s55, v150
	s_cmpk_lt_i32 s8, 0x500
	v_cmp_gt_i32_e32 vcc, s81, v136
	v_mad_i64_i32 v[168:169], s[0:1], v136, s90, v[138:139]
	s_cselect_b64 s[64:65], -1, 0
	s_and_b64 s[0:1], s[64:65], vcc
	s_cmpk_lt_i32 s8, 0x400
	s_cselect_b64 s[6:7], -1, 0
	s_ashr_i32 s9, s8, 31
	s_lshl_b64 s[70:71], s[8:9], 1
	v_cndmask_b32_e64 v136, v152, v158, s[2:3]
	v_lshlrev_b32_e32 v136, 7, v136
	v_lshl_add_u64 v[170:171], v[140:141], 0, v[136:137]
	s_waitcnt vmcnt(0)
; __device__ __forceinline__ unsigned pk2(float lo, float hi) { f32x2 v = {lo, hi}; nbf2 r = __builtin_convertvector(v, nbf2); return __builtin_bit_cast(unsigned, r); }
;     __device__ __forceinline__ void operator()(f32x4 (&acc)[2][2][4][2], const pg8::Unit& u, int wr, int wc, int fr, int fq, LAS unsigned char* lds) const {
;     ...
;         for (int ai = 0; ai < 2; ++ai)
; #pragma unroll
;             for (int m = 0; m < 4; ++m) {
;                 const int r = u.pm * 256 + ai * 128 + wr * 64 + m * 16 + fr;
;                 const bool lat = r < NLAT;
;                 const int t = r & (SEQ - 1);
;                 const int val = (wc & 1) ? (t & 63) : (t >> 6);
;                 const f32x4 cs = *(const f32x4*)(rope + val * 32 + 4 * fq), sn = *(const f32x4*)(rope + val * 32 + 16 + 4 * fq);
;                 bf16_t* rowp = O + (size_t)r * NQKVZ;
; #pragma unroll
;                 for (int bj = 0; bj < 2; ++bj) {
;                     const int cb = u.pn * 256 + bj * 128 + wc * 32;
;                     f32x4 t1 = acc[ai][bj][m][0], t2 = acc[ai][bj][m][1];
;                     if (cb < 1280 && lat) { const f32x4 o1 = t1 * cs - t2 * sn, o2 = t2 * cs + t1 * sn; t1 = o1; t2 = o2; }
;                     if (cb < 1024) { t1 = t1 * qs; t2 = t2 * qs; }
;                     u32x4 w; w.x = pk2(t1[0], t1[1]); w.y = pk2(t1[2], t1[3]); w.z = pk2(t2[0], t2[1]); w.w = pk2(t2[2], t2[3]);
;                     *(u32x4*)(rowp + cb + 8 * fq) = w;
;                 }
	v_pk_mul_f32 v[172:173], v[122:123], v[162:163]
	v_pk_mul_f32 v[174:175], v[120:121], v[160:161]
	v_pk_mul_f32 v[176:177], v[126:127], v[162:163]
	v_pk_mul_f32 v[178:179], v[124:125], v[160:161]
	v_pk_fma_f32 v[172:173], v[126:127], v[166:167], v[172:173] neg_lo:[0,0,1] neg_hi:[0,0,1]
	v_pk_fma_f32 v[174:175], v[124:125], v[164:165], v[174:175] neg_lo:[0,0,1] neg_hi:[0,0,1]
	v_pk_fma_f32 v[176:177], v[122:123], v[166:167], v[176:177]
	v_pk_fma_f32 v[178:179], v[120:121], v[164:165], v[178:179]
	s_or_b32 s0, s8, 0x80
	v_pk_mul_f32 v[180:181], v[114:115], v[162:163]
	v_pk_mul_f32 v[182:183], v[112:113], v[160:161]
	v_pk_mul_f32 v[162:163], v[118:119], v[162:163]
	v_pk_mul_f32 v[160:161], v[116:117], v[160:161]
	s_cmpk_lt_i32 s0, 0x500
	v_pk_fma_f32 v[180:181], v[118:119], v[166:167], v[180:181] neg_lo:[0,0,1] neg_hi:[0,0,1]
	v_pk_fma_f32 v[182:183], v[116:117], v[164:165], v[182:183] neg_lo:[0,0,1] neg_hi:[0,0,1]
	v_pk_fma_f32 v[162:163], v[114:115], v[166:167], v[162:163]
	v_pk_fma_f32 v[160:161], v[112:113], v[164:165], v[160:161]
	s_cselect_b64 s[66:67], -1, 0
	s_and_b64 vcc, s[66:67], vcc
	v_cvt_pk_bf16_f32 v120, v174, v175
	v_cvt_pk_bf16_f32 v121, v172, v173
	v_cvt_pk_bf16_f32 v122, v178, v179
	v_cvt_pk_bf16_f32 v123, v176, v177
	v_lshl_add_u64 v[124:125], v[168:169], 0, s[70:71]
	s_cmpk_lt_i32 s0, 0x400
	global_store_dwordx4 v[124:125], v[120:123], off
	s_nop 1
	s_cselect_b64 s[8:9], -1, 0
	v_cvt_pk_bf16_f32 v112, v182, v183
	v_cvt_pk_bf16_f32 v113, v180, v181
	v_cvt_pk_bf16_f32 v114, v160, v161
	v_cvt_pk_bf16_f32 v115, v162, v163
	global_store_dwordx4 v[124:125], v[112:115], off offset:256
	s_nop 1
	global_load_dwordx4 v[112:115], v[170:171], off offset:64
	s_nop 0
	global_load_dwordx4 v[116:119], v[170:171], off
	v_or_b32_e32 v120, s55, v152
	v_cmp_gt_i32_e32 vcc, s81, v120
	v_mad_i64_i32 v[120:121], s[0:1], v120, s90, v[138:139]
	s_and_b64 s[0:1], s[64:65], vcc
	s_and_b64 vcc, s[66:67], vcc
	v_cndmask_b32_e64 v122, v153, v158, s[2:3]
	v_lshlrev_b32_e32 v136, 7, v122
	v_lshl_add_u64 v[120:121], v[120:121], 0, s[70:71]
	v_lshl_add_u64 v[122:123], v[140:141], 0, v[136:137]
	s_waitcnt vmcnt(1)
	v_pk_mul_f32 v[124:125], v[106:107], v[114:115]
	v_pk_mul_f32 v[126:127], v[104:105], v[112:113]
	v_pk_mul_f32 v[160:161], v[110:111], v[114:115]
	v_pk_mul_f32 v[162:163], v[108:109], v[112:113]
	v_pk_mul_f32 v[164:165], v[98:99], v[114:115]
	v_pk_mul_f32 v[166:167], v[96:97], v[112:113]
	v_pk_mul_f32 v[114:115], v[102:103], v[114:115]
	v_pk_mul_f32 v[112:113], v[100:101], v[112:113]
	s_waitcnt vmcnt(0)
	v_pk_fma_f32 v[124:125], v[110:111], v[118:119], v[124:125] neg_lo:[0,0,1] neg_hi:[0,0,1]
	v_pk_fma_f32 v[126:127], v[108:109], v[116:117], v[126:127] neg_lo:[0,0,1] neg_hi:[0,0,1]
	v_pk_fma_f32 v[160:161], v[106:107], v[118:119], v[160:161]
	v_pk_fma_f32 v[162:163], v[104:105], v[116:117], v[162:163]
	v_pk_fma_f32 v[164:165], v[102:103], v[118:119], v[164:165] neg_lo:[0,0,1] neg_hi:[0,0,1]
	v_pk_fma_f32 v[166:167], v[100:101], v[116:117], v[166:167] neg_lo:[0,0,1] neg_hi:[0,0,1]
	v_pk_fma_f32 v[114:115], v[98:99], v[118:119], v[114:115]
	v_pk_fma_f32 v[112:113], v[96:97], v[116:117], v[112:113]
	v_mov_b32_e32 v96, v112
	v_mov_b32_e32 v97, v113
	v_mov_b32_e32 v113, v114
	v_mov_b32_e32 v112, v115
	v_mov_b32_e32 v115, v96
	v_cvt_pk_bf16_f32 v96, v126, v127
	v_mov_b32_e32 v114, v97
	v_cvt_pk_bf16_f32 v97, v124, v125
	v_cvt_pk_bf16_f32 v98, v162, v163
	v_cvt_pk_bf16_f32 v99, v160, v161
	v_cvt_pk_bf16_f32 v100, v166, v167
	v_cvt_pk_bf16_f32 v101, v164, v165
	v_cvt_pk_bf16_f32 v102, v115, v114
	v_cvt_pk_bf16_f32 v103, v113, v112
	global_store_dwordx4 v[120:121], v[96:99], off
	s_nop 1
	global_store_dwordx4 v[120:121], v[100:103], off offset:256
	s_nop 1
	global_load_dwordx4 v[96:99], v[122:123], off offset:64
	s_nop 0
	global_load_dwordx4 v[100:103], v[122:123], off
	v_or_b32_e32 v104, s55, v153
	v_cmp_gt_i32_e32 vcc, s81, v104
	v_mad_i64_i32 v[104:105], s[0:1], v104, s90, v[138:139]
	s_and_b64 s[0:1], s[64:65], vcc
	s_and_b64 vcc, s[66:67], vcc
	v_cndmask_b32_e64 v106, v154, v158, s[2:3]
	v_lshlrev_b32_e32 v136, 7, v106
	v_lshl_add_u64 v[104:105], v[104:105], 0, s[70:71]
	v_lshl_add_u64 v[106:107], v[140:141], 0, v[136:137]
	s_waitcnt vmcnt(1)
	v_pk_mul_f32 v[108:109], v[90:91], v[98:99]
	v_pk_mul_f32 v[110:111], v[88:89], v[96:97]
	v_pk_mul_f32 v[112:113], v[94:95], v[98:99]
	v_pk_mul_f32 v[114:115], v[92:93], v[96:97]
	v_pk_mul_f32 v[116:117], v[82:83], v[98:99]
	v_pk_mul_f32 v[118:119], v[80:81], v[96:97]
	v_pk_mul_f32 v[98:99], v[86:87], v[98:99]
	v_pk_mul_f32 v[96:97], v[84:85], v[96:97]
	s_waitcnt vmcnt(0)
	v_pk_fma_f32 v[108:109], v[94:95], v[102:103], v[108:109] neg_lo:[0,0,1] neg_hi:[0,0,1]
	v_pk_fma_f32 v[110:111], v[92:93], v[100:101], v[110:111] neg_lo:[0,0,1] neg_hi:[0,0,1]
	v_pk_fma_f32 v[112:113], v[90:91], v[102:103], v[112:113]
	v_pk_fma_f32 v[114:115], v[88:89], v[100:101], v[114:115]
	v_pk_fma_f32 v[116:117], v[86:87], v[102:103], v[116:117] neg_lo:[0,0,1] neg_hi:[0,0,1]
	v_pk_fma_f32 v[118:119], v[84:85], v[100:101], v[118:119] neg_lo:[0,0,1] neg_hi:[0,0,1]
	v_pk_fma_f32 v[98:99], v[82:83], v[102:103], v[98:99]
	v_pk_fma_f32 v[96:97], v[80:81], v[100:101], v[96:97]
	v_mov_b32_e32 v80, v96
	v_mov_b32_e32 v81, v97
	v_mov_b32_e32 v97, v98
	v_mov_b32_e32 v96, v99
	v_mov_b32_e32 v99, v80
	v_cvt_pk_bf16_f32 v80, v110, v111
	v_mov_b32_e32 v98, v81
	v_cvt_pk_bf16_f32 v81, v108, v109
	v_cvt_pk_bf16_f32 v82, v114, v115
	v_cvt_pk_bf16_f32 v83, v112, v113
	v_cvt_pk_bf16_f32 v84, v118, v119
	v_cvt_pk_bf16_f32 v85, v116, v117
	v_cvt_pk_bf16_f32 v86, v99, v98
	v_cvt_pk_bf16_f32 v87, v97, v96
	global_store_dwordx4 v[104:105], v[80:83], off
	s_nop 1
	global_store_dwordx4 v[104:105], v[84:87], off offset:256
	s_nop 1
	global_load_dwordx4 v[82:85], v[106:107], off offset:64
	s_nop 0
	global_load_dwordx4 v[86:89], v[106:107], off
	v_or_b32_e32 v80, s55, v154
	v_cmp_gt_i32_e32 vcc, s81, v80
	v_mad_i64_i32 v[80:81], s[0:1], v80, s90, v[138:139]
	s_addk_i32 s55, 0x80
	s_bfe_u32 s0, s55, 0x60006
	v_lshl_add_u64 v[90:91], v[80:81], 0, s[70:71]
	v_mov_b32_e32 v80, s0
	s_and_b64 s[0:1], s[64:65], vcc
	s_and_b64 vcc, s[66:67], vcc
	v_cndmask_b32_e64 v81, v150, v80, s[2:3]
	v_lshlrev_b32_e32 v136, 7, v81
	v_lshl_add_u64 v[92:93], v[140:141], 0, v[136:137]
	s_waitcnt vmcnt(1)
; __device__ __forceinline__ unsigned pk2(float lo, float hi) { f32x2 v = {lo, hi}; nbf2 r = __builtin_convertvector(v, nbf2); return __builtin_bit_cast(unsigned, r); }
;     __device__ __forceinline__ void operator()(f32x4 (&acc)[2][2][4][2], const pg8::Unit& u, int wr, int wc, int fr, int fq, LAS unsigned char* lds) const {
;     ...
;         for (int ai = 0; ai < 2; ++ai)
; #pragma unroll
;             for (int m = 0; m < 4; ++m) {
;                 const int r = u.pm * 256 + ai * 128 + wr * 64 + m * 16 + fr;
;                 const bool lat = r < NLAT;
;                 const int t = r & (SEQ - 1);
;                 const int val = (wc & 1) ? (t & 63) : (t >> 6);
;                 const f32x4 cs = *(const f32x4*)(rope + val * 32 + 4 * fq), sn = *(const f32x4*)(rope + val * 32 + 16 + 4 * fq);
;                 bf16_t* rowp = O + (size_t)r * NQKVZ;
; #pragma unroll
;                 for (int bj = 0; bj < 2; ++bj) {
;                     const int cb = u.pn * 256 + bj * 128 + wc * 32;
;                     f32x4 t1 = acc[ai][bj][m][0], t2 = acc[ai][bj][m][1];
;                     if (cb < 1280 && lat) { const f32x4 o1 = t1 * cs - t2 * sn, o2 = t2 * cs + t1 * sn; t1 = o1; t2 = o2; }
;                     if (cb < 1024) { t1 = t1 * qs; t2 = t2 * qs; }
;                     u32x4 w; w.x = pk2(t1[0], t1[1]); w.y = pk2(t1[2], t1[3]); w.z = pk2(t2[0], t2[1]); w.w = pk2(t2[2], t2[3]);
;                     *(u32x4*)(rowp + cb + 8 * fq) = w;
;                 }
	v_pk_mul_f32 v[94:95], v[74:75], v[84:85]
	v_pk_mul_f32 v[96:97], v[72:73], v[82:83]
	v_pk_mul_f32 v[98:99], v[78:79], v[84:85]
	v_pk_mul_f32 v[100:101], v[76:77], v[82:83]
	v_pk_mul_f32 v[102:103], v[66:67], v[84:85]
	v_pk_mul_f32 v[104:105], v[64:65], v[82:83]
	v_pk_mul_f32 v[84:85], v[70:71], v[84:85]
	v_pk_mul_f32 v[82:83], v[68:69], v[82:83]
	s_waitcnt vmcnt(0)
	v_pk_fma_f32 v[94:95], v[78:79], v[88:89], v[94:95] neg_lo:[0,0,1] neg_hi:[0,0,1]
	v_pk_fma_f32 v[96:97], v[76:77], v[86:87], v[96:97] neg_lo:[0,0,1] neg_hi:[0,0,1]
	v_pk_fma_f32 v[98:99], v[74:75], v[88:89], v[98:99]
	v_pk_fma_f32 v[100:101], v[72:73], v[86:87], v[100:101]
	v_pk_fma_f32 v[102:103], v[70:71], v[88:89], v[102:103] neg_lo:[0,0,1] neg_hi:[0,0,1]
	v_pk_fma_f32 v[104:105], v[68:69], v[86:87], v[104:105] neg_lo:[0,0,1] neg_hi:[0,0,1]
	v_pk_fma_f32 v[84:85], v[66:67], v[88:89], v[84:85]
	v_pk_fma_f32 v[82:83], v[64:65], v[86:87], v[82:83]
	v_mov_b32_e32 v64, v82
	v_mov_b32_e32 v82, v84
	v_mov_b32_e32 v84, v64
	v_cvt_pk_bf16_f32 v64, v96, v97
	v_cvt_pk_bf16_f32 v65, v94, v95
	v_cvt_pk_bf16_f32 v66, v100, v101
	v_cvt_pk_bf16_f32 v67, v98, v99
	v_cvt_pk_bf16_f32 v68, v104, v105
	v_cvt_pk_bf16_f32 v69, v102, v103
	v_cvt_pk_bf16_f32 v70, v84, v83
	v_cvt_pk_bf16_f32 v71, v82, v85
	global_store_dwordx4 v[90:91], v[64:67], off
	s_nop 1
	global_store_dwordx4 v[90:91], v[68:71], off offset:256
	s_nop 1
	global_load_dwordx4 v[64:67], v[92:93], off offset:64
	s_nop 0
	global_load_dwordx4 v[68:71], v[92:93], off
	v_or_b32_e32 v72, s55, v150
	v_cmp_gt_i32_e32 vcc, s81, v72
	v_mad_i64_i32 v[72:73], s[0:1], v72, s90, v[138:139]
	s_and_b64 s[0:1], s[64:65], vcc
	s_and_b64 vcc, s[66:67], vcc
	v_cndmask_b32_e64 v74, v152, v80, s[2:3]
	v_lshl_add_u64 v[72:73], v[72:73], 0, s[70:71]
	v_lshlrev_b32_e32 v136, 7, v74
	v_lshl_add_u64 v[74:75], v[140:141], 0, v[136:137]
	s_waitcnt vmcnt(1)
	v_pk_mul_f32 v[76:77], v[58:59], v[66:67]
	v_pk_mul_f32 v[78:79], v[56:57], v[64:65]
	v_pk_mul_f32 v[82:83], v[62:63], v[66:67]
	v_pk_mul_f32 v[84:85], v[60:61], v[64:65]
	v_pk_mul_f32 v[86:87], v[50:51], v[66:67]
	v_pk_mul_f32 v[88:89], v[48:49], v[64:65]
	v_pk_mul_f32 v[66:67], v[54:55], v[66:67]
	v_pk_mul_f32 v[64:65], v[52:53], v[64:65]
	s_waitcnt vmcnt(0)
	v_pk_fma_f32 v[76:77], v[62:63], v[70:71], v[76:77] neg_lo:[0,0,1] neg_hi:[0,0,1]
	v_pk_fma_f32 v[78:79], v[60:61], v[68:69], v[78:79] neg_lo:[0,0,1] neg_hi:[0,0,1]
	v_pk_fma_f32 v[82:83], v[58:59], v[70:71], v[82:83]
	v_pk_fma_f32 v[84:85], v[56:57], v[68:69], v[84:85]
	v_pk_fma_f32 v[86:87], v[54:55], v[70:71], v[86:87] neg_lo:[0,0,1] neg_hi:[0,0,1]
	v_pk_fma_f32 v[88:89], v[52:53], v[68:69], v[88:89] neg_lo:[0,0,1] neg_hi:[0,0,1]
	v_pk_fma_f32 v[66:67], v[50:51], v[70:71], v[66:67]
	v_pk_fma_f32 v[64:65], v[48:49], v[68:69], v[64:65]
	v_mov_b32_e32 v48, v64
	v_mov_b32_e32 v49, v65
	v_mov_b32_e32 v65, v66
	v_mov_b32_e32 v64, v67
	v_mov_b32_e32 v67, v48
	v_cvt_pk_bf16_f32 v48, v78, v79
	v_mov_b32_e32 v66, v49
	v_cvt_pk_bf16_f32 v49, v76, v77
	v_cvt_pk_bf16_f32 v50, v84, v85
	v_cvt_pk_bf16_f32 v51, v82, v83
	v_cvt_pk_bf16_f32 v52, v88, v89
	v_cvt_pk_bf16_f32 v53, v86, v87
	v_cvt_pk_bf16_f32 v54, v67, v66
	v_cvt_pk_bf16_f32 v55, v65, v64
	global_store_dwordx4 v[72:73], v[48:51], off
	s_nop 1
	global_store_dwordx4 v[72:73], v[52:55], off offset:256
	s_nop 1
	global_load_dwordx4 v[48:51], v[74:75], off offset:64
	s_nop 0
	global_load_dwordx4 v[52:55], v[74:75], off
	v_or_b32_e32 v56, s55, v152
	v_cmp_gt_i32_e32 vcc, s81, v56
	v_mad_i64_i32 v[56:57], s[0:1], v56, s90, v[138:139]
	s_and_b64 s[0:1], s[64:65], vcc
	s_and_b64 vcc, s[66:67], vcc
	v_cndmask_b32_e64 v58, v153, v80, s[2:3]
	v_lshl_add_u64 v[56:57], v[56:57], 0, s[70:71]
	v_lshlrev_b32_e32 v136, 7, v58
	v_lshl_add_u64 v[58:59], v[140:141], 0, v[136:137]
	s_waitcnt vmcnt(1)
	v_pk_mul_f32 v[60:61], v[42:43], v[50:51]
	v_pk_mul_f32 v[62:63], v[40:41], v[48:49]
	v_pk_mul_f32 v[64:65], v[46:47], v[50:51]
	v_pk_mul_f32 v[66:67], v[44:45], v[48:49]
	v_pk_mul_f32 v[68:69], v[34:35], v[50:51]
	v_pk_mul_f32 v[70:71], v[32:33], v[48:49]
	v_pk_mul_f32 v[50:51], v[38:39], v[50:51]
	v_pk_mul_f32 v[48:49], v[36:37], v[48:49]
	s_waitcnt vmcnt(0)
; __device__ __forceinline__ unsigned pk2(float lo, float hi) { f32x2 v = {lo, hi}; nbf2 r = __builtin_convertvector(v, nbf2); return __builtin_bit_cast(unsigned, r); }
;     __device__ __forceinline__ void operator()(f32x4 (&acc)[2][2][4][2], const pg8::Unit& u, int wr, int wc, int fr, int fq, LAS unsigned char* lds) const {
;     ...
;         for (int ai = 0; ai < 2; ++ai)
; #pragma unroll
;             for (int m = 0; m < 4; ++m) {
;                 const int r = u.pm * 256 + ai * 128 + wr * 64 + m * 16 + fr;
;                 const bool lat = r < NLAT;
;                 const int t = r & (SEQ - 1);
;                 const int val = (wc & 1) ? (t & 63) : (t >> 6);
;                 const f32x4 cs = *(const f32x4*)(rope + val * 32 + 4 * fq), sn = *(const f32x4*)(rope + val * 32 + 16 + 4 * fq);
;                 bf16_t* rowp = O + (size_t)r * NQKVZ;
; #pragma unroll
;                 for (int bj = 0; bj < 2; ++bj) {
;                     const int cb = u.pn * 256 + bj * 128 + wc * 32;
;                     f32x4 t1 = acc[ai][bj][m][0], t2 = acc[ai][bj][m][1];
;                     if (cb < 1280 && lat) { const f32x4 o1 = t1 * cs - t2 * sn, o2 = t2 * cs + t1 * sn; t1 = o1; t2 = o2; }
;                     if (cb < 1024) { t1 = t1 * qs; t2 = t2 * qs; }
;                     u32x4 w; w.x = pk2(t1[0], t1[1]); w.y = pk2(t1[2], t1[3]); w.z = pk2(t2[0], t2[1]); w.w = pk2(t2[2], t2[3]);
;                     *(u32x4*)(rowp + cb + 8 * fq) = w;
;                 }
	v_pk_fma_f32 v[60:61], v[46:47], v[54:55], v[60:61] neg_lo:[0,0,1] neg_hi:[0,0,1]
	v_pk_fma_f32 v[62:63], v[44:45], v[52:53], v[62:63] neg_lo:[0,0,1] neg_hi:[0,0,1]
	v_pk_fma_f32 v[64:65], v[42:43], v[54:55], v[64:65]
	v_pk_fma_f32 v[66:67], v[40:41], v[52:53], v[66:67]
	v_pk_fma_f32 v[68:69], v[38:39], v[54:55], v[68:69] neg_lo:[0,0,1] neg_hi:[0,0,1]
	v_pk_fma_f32 v[70:71], v[36:37], v[52:53], v[70:71] neg_lo:[0,0,1] neg_hi:[0,0,1]
	v_pk_fma_f32 v[50:51], v[34:35], v[54:55], v[50:51]
	v_pk_fma_f32 v[48:49], v[32:33], v[52:53], v[48:49]
	v_mov_b32_e32 v32, v48
	v_mov_b32_e32 v33, v49
	v_mov_b32_e32 v49, v50
	v_mov_b32_e32 v48, v51
	v_mov_b32_e32 v51, v32
	v_cvt_pk_bf16_f32 v32, v62, v63
	v_mov_b32_e32 v50, v33
	v_cvt_pk_bf16_f32 v33, v60, v61
	v_cvt_pk_bf16_f32 v34, v66, v67
	v_cvt_pk_bf16_f32 v35, v64, v65
	v_cvt_pk_bf16_f32 v36, v70, v71
	v_cvt_pk_bf16_f32 v37, v68, v69
	v_cvt_pk_bf16_f32 v38, v51, v50
	v_cvt_pk_bf16_f32 v39, v49, v48
	global_store_dwordx4 v[56:57], v[32:35], off
	s_nop 1
	global_store_dwordx4 v[56:57], v[36:39], off offset:256
	s_nop 1
	global_load_dwordx4 v[32:35], v[58:59], off offset:64
	s_nop 0
	global_load_dwordx4 v[36:39], v[58:59], off
	v_or_b32_e32 v40, s55, v153
	v_cmp_gt_i32_e32 vcc, s81, v40
	v_mad_i64_i32 v[40:41], s[0:1], v40, s90, v[138:139]
	s_and_b64 s[0:1], s[64:65], vcc
	s_and_b64 vcc, s[66:67], vcc
	v_cndmask_b32_e64 v42, v154, v80, s[2:3]
	v_lshl_add_u64 v[40:41], v[40:41], 0, s[70:71]
	v_lshlrev_b32_e32 v136, 7, v42
	v_lshl_add_u64 v[42:43], v[140:141], 0, v[136:137]
	s_waitcnt vmcnt(1)
	v_pk_mul_f32 v[44:45], v[26:27], v[34:35]
	v_pk_mul_f32 v[46:47], v[24:25], v[32:33]
	v_pk_mul_f32 v[48:49], v[30:31], v[34:35]
	v_pk_mul_f32 v[50:51], v[28:29], v[32:33]
	v_pk_mul_f32 v[52:53], v[18:19], v[34:35]
	v_pk_mul_f32 v[54:55], v[16:17], v[32:33]
	v_pk_mul_f32 v[34:35], v[22:23], v[34:35]
	v_pk_mul_f32 v[32:33], v[20:21], v[32:33]
	s_waitcnt vmcnt(0)
	v_pk_fma_f32 v[44:45], v[30:31], v[38:39], v[44:45] neg_lo:[0,0,1] neg_hi:[0,0,1]
	v_pk_fma_f32 v[46:47], v[28:29], v[36:37], v[46:47] neg_lo:[0,0,1] neg_hi:[0,0,1]
	v_pk_fma_f32 v[48:49], v[26:27], v[38:39], v[48:49]
	v_pk_fma_f32 v[50:51], v[24:25], v[36:37], v[50:51]
	v_pk_fma_f32 v[52:53], v[22:23], v[38:39], v[52:53] neg_lo:[0,0,1] neg_hi:[0,0,1]
	v_pk_fma_f32 v[54:55], v[20:21], v[36:37], v[54:55] neg_lo:[0,0,1] neg_hi:[0,0,1]
	v_pk_fma_f32 v[34:35], v[18:19], v[38:39], v[34:35]
	v_pk_fma_f32 v[32:33], v[16:17], v[36:37], v[32:33]
	v_mov_b32_e32 v16, v32
	v_mov_b32_e32 v17, v33
	v_mov_b32_e32 v33, v34
	v_mov_b32_e32 v32, v35
	v_mov_b32_e32 v35, v16
	v_cvt_pk_bf16_f32 v16, v46, v47
	v_mov_b32_e32 v34, v17
	v_cvt_pk_bf16_f32 v17, v44, v45
	v_cvt_pk_bf16_f32 v18, v50, v51
	v_cvt_pk_bf16_f32 v19, v48, v49
	v_cvt_pk_bf16_f32 v20, v54, v55
	v_cvt_pk_bf16_f32 v21, v52, v53
	v_cvt_pk_bf16_f32 v22, v35, v34
	v_cvt_pk_bf16_f32 v23, v33, v32
	global_store_dwordx4 v[40:41], v[16:19], off
	s_nop 1
	global_store_dwordx4 v[40:41], v[20:23], off offset:256
	s_nop 1
	global_load_dwordx4 v[16:19], v[42:43], off offset:64
	s_nop 0
	global_load_dwordx4 v[20:23], v[42:43], off
	v_or_b32_e32 v24, s55, v154
	s_andn2_b64 vcc, exec, s[4:5]
	v_cmp_gt_i32_e64 s[0:1], s81, v24
	v_mad_i64_i32 v[24:25], s[4:5], v24, s90, v[138:139]
	s_and_b64 s[4:5], s[64:65], s[0:1]
	s_and_b64 s[0:1], s[66:67], s[0:1]
	v_lshl_add_u64 v[24:25], v[24:25], 0, s[70:71]
	s_waitcnt vmcnt(1)
	v_pk_mul_f32 v[26:27], v[10:11], v[18:19]
	v_pk_mul_f32 v[28:29], v[8:9], v[16:17]
	v_pk_mul_f32 v[30:31], v[14:15], v[18:19]
	v_pk_mul_f32 v[32:33], v[12:13], v[16:17]
	v_pk_mul_f32 v[34:35], v[2:3], v[18:19]
	v_pk_mul_f32 v[36:37], v[0:1], v[16:17]
	v_pk_mul_f32 v[18:19], v[6:7], v[18:19]
	v_pk_mul_f32 v[16:17], v[4:5], v[16:17]
	s_waitcnt vmcnt(0)
	v_pk_fma_f32 v[26:27], v[14:15], v[22:23], v[26:27] neg_lo:[0,0,1] neg_hi:[0,0,1]
	v_pk_fma_f32 v[28:29], v[12:13], v[20:21], v[28:29] neg_lo:[0,0,1] neg_hi:[0,0,1]
	v_pk_fma_f32 v[30:31], v[10:11], v[22:23], v[30:31]
	v_pk_fma_f32 v[32:33], v[8:9], v[20:21], v[32:33]
	v_pk_fma_f32 v[34:35], v[6:7], v[22:23], v[34:35] neg_lo:[0,0,1] neg_hi:[0,0,1]
	v_pk_fma_f32 v[36:37], v[4:5], v[20:21], v[36:37] neg_lo:[0,0,1] neg_hi:[0,0,1]
	v_pk_fma_f32 v[18:19], v[2:3], v[22:23], v[18:19]
	v_pk_fma_f32 v[16:17], v[0:1], v[20:21], v[16:17]
	v_mov_b32_e32 v0, v16
	v_mov_b32_e32 v1, v17
	v_mov_b32_e32 v17, v18
	v_mov_b32_e32 v16, v19
	v_mov_b32_e32 v19, v0
	v_cvt_pk_bf16_f32 v0, v28, v29
	v_mov_b32_e32 v18, v1
	v_cvt_pk_bf16_f32 v1, v26, v27
	v_cvt_pk_bf16_f32 v2, v32, v33
	v_cvt_pk_bf16_f32 v3, v30, v31
	s_mov_b64 s[0:1], -1
	v_cvt_pk_bf16_f32 v4, v36, v37
	v_cvt_pk_bf16_f32 v5, v34, v35
	v_cvt_pk_bf16_f32 v6, v19, v18
	v_cvt_pk_bf16_f32 v7, v17, v16
	global_store_dwordx4 v[24:25], v[0:3], off
	s_nop 1
	global_store_dwordx4 v[24:25], v[4:7], off offset:256
	s_nop 1
	s_cbranch_vccnz .LBB0_181
	s_andn2_b64 vcc, exec, s[42:43]
	s_cbranch_vccnz .LBB0_180
	s_barrier
	s_branch .LBB0_180
